# speedup vs baseline: 1.0210x; 1.0131x over previous
; #define LAS __attribute__((address_space(3)))
; __device__ __forceinline__ unsigned xb_add(unsigned* p, unsigned v) { return __hip_atomic_fetch_add(p, v, __ATOMIC_RELAXED, __HIP_MEMORY_SCOPE_AGENT); }
; __device__ __forceinline__ unsigned xb_xcc_id() { return (unsigned)__builtin_amdgcn_s_getreg((3 << 11) | 20) & 0xFu; }
; __global__ __launch_bounds__(512, 2) void mk_fwd(Params p, int ph_lo, int ph_hi) {
;     extern __shared__ __attribute__((aligned(16))) unsigned char shm[];
;     LAS unsigned char* lds = (LAS unsigned char*)shm;
;     volatile LAS unsigned* st = (volatile LAS unsigned*)(lds + LDS_STATE);
;     unsigned* bar = (unsigned*)(p.ws + WS_CTL);
;     XcdBarrier xb; xb.bar = bar; xb.x = xb_xcc_id(); xb.st = st;
;     if (threadIdx.x == 0) { st[0] = 0u; st[1] = 0u; st[2] = blockIdx.x; st[3] = xb_add(&bar[XB_XCNT(xb.x)], 1u); }
_Z6mk_fwd6Paramsii:
	s_load_dwordx2 s[46:47], s[0:1], 0xa0
	s_load_dwordx8 s[36:43], s[0:1], 0x80
	s_mov_b32 s84, s2
	s_getreg_b32 s2, hwreg(HW_REG_XCC_ID, 0, 4)
	v_and_b32_e32 v200, 0x3ff, v0
	s_waitcnt lgkmcnt(0)
	v_readfirstlane_b32 s3, v200
	s_nop 3
	s_lshr_b32 s3, s3, 6
	s_cmp_ge_u32 s3, 4
	s_cbranch_scc0 .Lprio_skip
	s_setprio 1
.Lprio_skip:
	s_add_u32 s4, s46, 0x2ada1000
	s_addc_u32 s5, s47, 0
	s_and_b32 s2, s2, 15
	v_writelane_b32 v249, s2, 0
	v_cmp_eq_u32_e64 s[6:7], 0, v200
	s_mov_b64 s[2:3], exec
	s_nop 0
	v_writelane_b32 v249, s6, 1
	s_nop 1
	v_writelane_b32 v249, s7, 2
	s_and_b64 s[6:7], s[2:3], s[6:7]
	s_mov_b64 exec, s[6:7]
	s_cbranch_execz .LBB0_4
	s_add_i32 s8, 0, 0x20000
	v_mov_b32_e32 v1, 0
	v_mov_b32_e32 v2, s8
	s_add_i32 s8, 0, 0x20004
	ds_write_b32 v2, v1
	v_mov_b32_e32 v2, s8
	s_add_i32 s8, 0, 0x20008
	s_mov_b64 s[6:7], exec
	ds_write_b32 v2, v1
	v_mov_b32_e32 v1, s8
	v_mov_b32_e32 v2, s84
	ds_write_b32 v1, v2
	v_mbcnt_lo_u32_b32 v1, s6, 0
	v_mbcnt_hi_u32_b32 v1, s7, v1
	v_cmp_eq_u32_e32 vcc, 0, v1
	s_and_saveexec_b64 s[8:9], vcc
	s_cbranch_execz .LBB0_3
	v_readlane_b32 s10, v249, 0
	s_lshl_b32 s10, s10, 8
	s_bcnt1_i32_b64 s6, s[6:7]
	v_mov_b32_e32 v2, s10
	v_mov_b32_e32 v3, s6
	global_atomic_add v2, v2, v3, s[4:5] offset:1024 sc0
